# B-mixer pair epilogue (no SiLU) routed through the hand-written fast path; compiler epilogue body removed
# speedup vs baseline: 1.0152x; 1.0152x over previous
; #define PG8_STAGE(bufoff, gbase, voff) do { _Pragma("unroll") for (int _i = 0; _i < 2; ++_i) { \
;         const unsigned _m0 = ldsb + (unsigned)((bufoff) + _i * 8192); const char* _gb = (const char*)(gbase); \
;         asm volatile("s_mov_b32 m0, %0\n\ts_nop 0\n\tglobal_load_lds_dwordx4 %1, %2" :: "s"(_m0), "v"((voff)[_i]), "s"(_gb) : "m0", "memory"); } } while (0)
; #define PG8_LDA(dst, b, h) do { _Pragma("unroll") for (int m = 0; m < 4; ++m) _Pragma("unroll") for (int k = 0; k < 2; ++k) dst[m][k] = *(const LAS bf16x8*)(lds + PG8_SA(b, h) + aoff + m * 2048 + k * 1024); } while (0)
; #define PG8_LDB(dst, b, h) do { _Pragma("unroll") for (int n = 0; n < 2; ++n) _Pragma("unroll") for (int k = 0; k < 2; ++k) dst[n][k] = *(const LAS bf16x8*)(lds + PG8_SB(b, h) + boff + n * 2048 + k * 1024); } while (0)
; #define PG8_MMA(ai, bj, At, Bt) do { __builtin_amdgcn_s_setprio(1); _Pragma("unroll") for (int m = 0; m < 4; ++m) _Pragma("unroll") for (int n = 0; n < 2; ++n) _Pragma("unroll") for (int k = 0; k < 2; ++k) \
;         acc[ai][bj][m][n] = __builtin_amdgcn_mfma_f32_16x16x32_bf16(Bt[n][k], At[m][k], acc[ai][bj][m][n], 0, 0, 0); __builtin_amdgcn_s_setprio(0); } while (0)
; #define PG8_WAIT_V(n) asm volatile("s_waitcnt vmcnt(" #n ")" ::: "memory")
; #define PG8_WAIT_L(n) asm volatile("s_waitcnt lgkmcnt(" #n ")" ::: "memory")
; #define PG8_BAR __builtin_amdgcn_s_barrier()
; #define PG8_SCHED __builtin_amdgcn_sched_barrier(0)
; template <class Epi, bool ALIGN_EPI>
; __device__ __forceinline__ void gemm_phase(LAS unsigned char* lds, const Gemm g, const StaticOrder& S, const Epi& E) {
;     ...
;             PG8_LDB(B0, 0, 0); PG8_LDB(B1, 0, 1); PG8_SCHED; PG8_LDA(At, 0, 0); PG8_STAGE(PG8_SA(1, 1), a1 + hstepA, voffA);
;             PG8_WAIT_V(8); PG8_WAIT_L(0); PG8_BAR; PG8_MMA(0, 0, At, B0); PG8_MMA(0, 1, At, B1); PG8_BAR; PG8_SCHED;
;             PG8_LDA(At, 0, 1); PG8_STAGE(PG8_SB(0, 0), b2, voffB); PG8_STAGE(PG8_SB(0, 1), b2 + hstepB, voffB); PG8_STAGE(PG8_SA(0, 0), a2, voffA);
;             PG8_WAIT_V(8); PG8_WAIT_L(0); PG8_BAR; PG8_MMA(1, 0, At, B0); PG8_MMA(1, 1, At, B1); PG8_BAR; PG8_SCHED;
.LBB0_306:
	v_add_u32_e32 v134, 0x10000, v185
	v_add_u32_e32 v158, 0x14000, v185
	ds_read_b128 v[74:77], v134
	ds_read_b128 v[94:97], v134 offset:1024
	ds_read_b128 v[114:117], v134 offset:2048
	ds_read_b128 v[134:137], v134 offset:3072
	ds_read_b128 v[146:149], v158
	ds_read_b128 v[150:153], v158 offset:1024
	ds_read_b128 v[154:157], v158 offset:2048
	ds_read_b128 v[158:161], v158 offset:3072
	s_add_u32 s30, s92, 0xfffc0080
	s_addc_u32 s31, s93, -1
	s_cmp_eq_u32 s50, 12
	s_cselect_b32 s60, s5, s30
	s_cselect_b32 s61, s4, s31
	s_cselect_b32 s58, s37, s41
	s_cselect_b32 s59, s35, s49
	s_add_u32 s56, s60, 0x80
	s_addc_u32 s57, s61, 0
	ds_read_b128 v[162:165], v186
	ds_read_b128 v[166:169], v186 offset:1024
	ds_read_b128 v[170:173], v186 offset:2048
	ds_read_b128 v[174:177], v186 offset:3072
	ds_read_b128 v[188:191], v186 offset:4096
	ds_read_b128 v[202:205], v186 offset:5120
	ds_read_b128 v[206:209], v186 offset:6144
	ds_read_b128 v[210:213], v186 offset:7168
	s_mov_b32 m0, s67
	s_nop 0
	global_load_lds_dwordx4 v0, s[92:93]
	s_nop 0
	s_mov_b32 m0, s65
	s_nop 0
	global_load_lds_dwordx4 v181, s[92:93]
	s_waitcnt vmcnt(8)
	s_waitcnt lgkmcnt(0)
	s_barrier
	s_setprio 1
	s_waitcnt lgkmcnt(0)
	v_mfma_f32_16x16x32_bf16 v[142:145], v[74:77], v[162:165], v[142:145]
	v_mfma_f32_16x16x32_bf16 v[142:145], v[94:97], v[166:169], v[142:145]
	v_mfma_f32_16x16x32_bf16 v[138:141], v[114:117], v[162:165], v[138:141]
	v_mfma_f32_16x16x32_bf16 v[138:141], v[134:137], v[166:169], v[138:141]
	v_mfma_f32_16x16x32_bf16 v[130:133], v[146:149], v[162:165], v[130:133]
	v_mfma_f32_16x16x32_bf16 v[130:133], v[150:153], v[166:169], v[130:133]
	v_mfma_f32_16x16x32_bf16 v[126:129], v[154:157], v[162:165], v[126:129]
	v_mfma_f32_16x16x32_bf16 v[126:129], v[158:161], v[166:169], v[126:129]
	v_mfma_f32_16x16x32_bf16 v[106:109], v[154:157], v[170:173], v[106:109]
	v_mfma_f32_16x16x32_bf16 v[106:109], v[158:161], v[174:177], v[106:109]
	v_mfma_f32_16x16x32_bf16 v[110:113], v[146:149], v[170:173], v[110:113]
	v_mfma_f32_16x16x32_bf16 v[110:113], v[150:153], v[174:177], v[110:113]
	v_mfma_f32_16x16x32_bf16 v[118:121], v[114:117], v[170:173], v[118:121]
	v_mfma_f32_16x16x32_bf16 v[118:121], v[134:137], v[174:177], v[118:121]
	v_mfma_f32_16x16x32_bf16 v[122:125], v[74:77], v[170:173], v[122:125]
	v_mfma_f32_16x16x32_bf16 v[122:125], v[94:97], v[174:177], v[122:125]
	v_mfma_f32_16x16x32_bf16 v[102:105], v[74:77], v[188:191], v[102:105]
	v_mfma_f32_16x16x32_bf16 v[102:105], v[94:97], v[202:205], v[102:105]
	v_mfma_f32_16x16x32_bf16 v[98:101], v[114:117], v[188:191], v[98:101]
	v_mfma_f32_16x16x32_bf16 v[98:101], v[134:137], v[202:205], v[98:101]
	v_mfma_f32_16x16x32_bf16 v[90:93], v[146:149], v[188:191], v[90:93]
	v_mfma_f32_16x16x32_bf16 v[90:93], v[150:153], v[202:205], v[90:93]
	v_mfma_f32_16x16x32_bf16 v[86:89], v[154:157], v[188:191], v[86:89]
	v_mfma_f32_16x16x32_bf16 v[86:89], v[158:161], v[202:205], v[86:89]
	v_mfma_f32_16x16x32_bf16 v[66:69], v[154:157], v[206:209], v[66:69]
	v_mfma_f32_16x16x32_bf16 v[66:69], v[158:161], v[210:213], v[66:69]
	v_mfma_f32_16x16x32_bf16 v[70:73], v[146:149], v[206:209], v[70:73]
	v_mfma_f32_16x16x32_bf16 v[70:73], v[150:153], v[210:213], v[70:73]
	v_mfma_f32_16x16x32_bf16 v[78:81], v[114:117], v[206:209], v[78:81]
	v_mfma_f32_16x16x32_bf16 v[78:81], v[134:137], v[210:213], v[78:81]
	v_mfma_f32_16x16x32_bf16 v[82:85], v[74:77], v[206:209], v[82:85]
	v_mfma_f32_16x16x32_bf16 v[82:85], v[94:97], v[210:213], v[82:85]
	s_setprio 0
	s_barrier
	ds_read_b128 v[162:165], v186 offset:16384
	ds_read_b128 v[166:169], v186 offset:17408
	ds_read_b128 v[170:173], v186 offset:18432
	ds_read_b128 v[174:177], v186 offset:19456
	ds_read_b128 v[188:191], v186 offset:20480
	ds_read_b128 v[202:205], v186 offset:21504
	ds_read_b128 v[206:209], v186 offset:22528
	ds_read_b128 v[210:213], v186 offset:23552
	s_mov_b32 m0, s29
	s_nop 0
	global_load_lds_dwordx4 v180, s[58:59]
	s_add_u32 s30, s58, 0x40000
	s_mov_b32 m0, s42
	s_nop 0
	global_load_lds_dwordx4 v182, s[58:59]
	s_addc_u32 s31, s59, 0
	s_mov_b32 m0, s43
	s_nop 0
	global_load_lds_dwordx4 v180, s[30:31]
	s_nop 0
	s_mov_b32 m0, s44
	s_nop 0
	global_load_lds_dwordx4 v182, s[30:31]
	s_nop 0
	s_mov_b32 m0, s15
	s_nop 0
	global_load_lds_dwordx4 v0, s[60:61]
	s_nop 0
	s_mov_b32 m0, s45
	s_nop 0
	global_load_lds_dwordx4 v181, s[60:61]
	s_waitcnt vmcnt(8)
	s_waitcnt lgkmcnt(0)
	s_barrier
	s_setprio 1
	s_waitcnt lgkmcnt(0)
	v_mfma_f32_16x16x32_bf16 v[62:65], v[74:77], v[162:165], v[62:65]
	v_mfma_f32_16x16x32_bf16 v[62:65], v[94:97], v[166:169], v[62:65]
	v_mfma_f32_16x16x32_bf16 v[58:61], v[114:117], v[162:165], v[58:61]
	v_mfma_f32_16x16x32_bf16 v[58:61], v[134:137], v[166:169], v[58:61]
	v_mfma_f32_16x16x32_bf16 v[54:57], v[146:149], v[162:165], v[54:57]
	v_mfma_f32_16x16x32_bf16 v[54:57], v[150:153], v[166:169], v[54:57]
	v_mfma_f32_16x16x32_bf16 v[50:53], v[154:157], v[162:165], v[50:53]
	v_mfma_f32_16x16x32_bf16 v[50:53], v[158:161], v[166:169], v[50:53]
	v_mfma_f32_16x16x32_bf16 v[34:37], v[154:157], v[170:173], v[34:37]
	v_mfma_f32_16x16x32_bf16 v[34:37], v[158:161], v[174:177], v[34:37]
	v_mfma_f32_16x16x32_bf16 v[38:41], v[146:149], v[170:173], v[38:41]
	v_mfma_f32_16x16x32_bf16 v[38:41], v[150:153], v[174:177], v[38:41]
	v_mfma_f32_16x16x32_bf16 v[42:45], v[114:117], v[170:173], v[42:45]
	v_mfma_f32_16x16x32_bf16 v[42:45], v[134:137], v[174:177], v[42:45]
	v_mfma_f32_16x16x32_bf16 v[46:49], v[74:77], v[170:173], v[46:49]
	v_mfma_f32_16x16x32_bf16 v[46:49], v[94:97], v[174:177], v[46:49]
	v_mfma_f32_16x16x32_bf16 v[30:33], v[74:77], v[188:191], v[30:33]
	v_mfma_f32_16x16x32_bf16 v[30:33], v[94:97], v[202:205], v[30:33]
	v_mfma_f32_16x16x32_bf16 v[26:29], v[114:117], v[188:191], v[26:29]
	v_mfma_f32_16x16x32_bf16 v[26:29], v[134:137], v[202:205], v[26:29]
	v_mfma_f32_16x16x32_bf16 v[22:25], v[146:149], v[188:191], v[22:25]
	v_mfma_f32_16x16x32_bf16 v[22:25], v[150:153], v[202:205], v[22:25]
	v_mfma_f32_16x16x32_bf16 v[18:21], v[154:157], v[188:191], v[18:21]
	v_mfma_f32_16x16x32_bf16 v[18:21], v[158:161], v[202:205], v[18:21]
	v_mfma_f32_16x16x32_bf16 v[2:5], v[154:157], v[206:209], v[2:5]
	v_mfma_f32_16x16x32_bf16 v[2:5], v[158:161], v[210:213], v[2:5]
	v_mfma_f32_16x16x32_bf16 v[6:9], v[146:149], v[206:209], v[6:9]
	v_mfma_f32_16x16x32_bf16 v[6:9], v[150:153], v[210:213], v[6:9]
	v_mfma_f32_16x16x32_bf16 v[10:13], v[114:117], v[206:209], v[10:13]
	v_mfma_f32_16x16x32_bf16 v[10:13], v[134:137], v[210:213], v[10:13]
	v_mfma_f32_16x16x32_bf16 v[14:17], v[74:77], v[206:209], v[14:17]
	v_mfma_f32_16x16x32_bf16 v[14:17], v[94:97], v[210:213], v[14:17]
	s_setprio 0
	s_barrier
; #define PG8_STAGE(bufoff, gbase, voff) do { _Pragma("unroll") for (int _i = 0; _i < 2; ++_i) { \
;         const unsigned _m0 = ldsb + (unsigned)((bufoff) + _i * 8192); const char* _gb = (const char*)(gbase); \
;         asm volatile("s_mov_b32 m0, %0\n\ts_nop 0\n\tglobal_load_lds_dwordx4 %1, %2" :: "s"(_m0), "v"((voff)[_i]), "s"(_gb) : "m0", "memory"); } } while (0)
; #define PG8_LDA(dst, b, h) do { _Pragma("unroll") for (int m = 0; m < 4; ++m) _Pragma("unroll") for (int k = 0; k < 2; ++k) dst[m][k] = *(const LAS bf16x8*)(lds + PG8_SA(b, h) + aoff + m * 2048 + k * 1024); } while (0)
; #define PG8_LDB(dst, b, h) do { _Pragma("unroll") for (int n = 0; n < 2; ++n) _Pragma("unroll") for (int k = 0; k < 2; ++k) dst[n][k] = *(const LAS bf16x8*)(lds + PG8_SB(b, h) + boff + n * 2048 + k * 1024); } while (0)
; #define PG8_MMA(ai, bj, At, Bt) do { __builtin_amdgcn_s_setprio(1); _Pragma("unroll") for (int m = 0; m < 4; ++m) _Pragma("unroll") for (int n = 0; n < 2; ++n) _Pragma("unroll") for (int k = 0; k < 2; ++k) \
;         acc[ai][bj][m][n] = __builtin_amdgcn_mfma_f32_16x16x32_bf16(Bt[n][k], At[m][k], acc[ai][bj][m][n], 0, 0, 0); __builtin_amdgcn_s_setprio(0); } while (0)
; #define PG8_WAIT_V(n) asm volatile("s_waitcnt vmcnt(" #n ")" ::: "memory")
; #define PG8_WAIT_L(n) asm volatile("s_waitcnt lgkmcnt(" #n ")" ::: "memory")
; #define PG8_BAR __builtin_amdgcn_s_barrier()
; #define PG8_SCHED __builtin_amdgcn_sched_barrier(0)
; template <class Epi, bool ALIGN_EPI>
; __device__ __forceinline__ void gemm_phase(LAS unsigned char* lds, const Gemm g, const StaticOrder& S, const Epi& E) {
;     ...
;             PG8_LDB(B0, 1, 0); PG8_LDB(B1, 1, 1); PG8_SCHED; PG8_LDA(At, 1, 0); PG8_STAGE(PG8_SA(0, 1), a2 + hstepA, voffA);
;             PG8_WAIT_V(8); PG8_WAIT_L(0); PG8_BAR; PG8_MMA(0, 0, At, B0); PG8_MMA(0, 1, At, B1); PG8_BAR; PG8_SCHED;
;             PG8_LDA(At, 1, 1); PG8_STAGE(PG8_SB(1, 0), b3, voffB); PG8_STAGE(PG8_SB(1, 1), b3 + hstepB, voffB); PG8_STAGE(PG8_SA(1, 0), a3, voffA);
;             PG8_WAIT_V(8); PG8_WAIT_L(0); PG8_BAR; PG8_MMA(1, 0, At, B0); PG8_MMA(1, 1, At, B1); PG8_BAR; PG8_SCHED;
;         }
;         if constexpr (ALIGN_EPI) { if (wr == 0) PG8_BAR; }
	v_add_u32_e32 v134, 0x18000, v185
	v_add_u32_e32 v158, 0x1c000, v185
	ds_read_b128 v[74:77], v134
	ds_read_b128 v[94:97], v134 offset:1024
	ds_read_b128 v[114:117], v134 offset:2048
	ds_read_b128 v[134:137], v134 offset:3072
	ds_read_b128 v[146:149], v158
	ds_read_b128 v[150:153], v158 offset:1024
	ds_read_b128 v[154:157], v158 offset:2048
	ds_read_b128 v[158:161], v158 offset:3072
	ds_read_b128 v[162:165], v186 offset:32768
	ds_read_b128 v[166:169], v186 offset:33792
	ds_read_b128 v[170:173], v186 offset:34816
	ds_read_b128 v[174:177], v186 offset:35840
	ds_read_b128 v[188:191], v186 offset:36864
	ds_read_b128 v[202:205], v186 offset:37888
	ds_read_b128 v[206:209], v186 offset:38912
	ds_read_b128 v[210:213], v186 offset:39936
	s_add_u32 s30, s60, 0x40000
	s_addc_u32 s31, s61, 0
	s_mov_b32 m0, s55
	s_nop 0
	global_load_lds_dwordx4 v0, s[30:31]
	s_nop 0
	s_mov_b32 m0, s88
	s_nop 0
	global_load_lds_dwordx4 v181, s[30:31]
	s_waitcnt vmcnt(8)
	s_waitcnt lgkmcnt(0)
	s_barrier
	s_setprio 1
	s_waitcnt lgkmcnt(0)
	v_mfma_f32_16x16x32_bf16 v[142:145], v[74:77], v[162:165], v[142:145]
	v_mfma_f32_16x16x32_bf16 v[142:145], v[94:97], v[166:169], v[142:145]
	v_mfma_f32_16x16x32_bf16 v[138:141], v[114:117], v[162:165], v[138:141]
	v_mfma_f32_16x16x32_bf16 v[138:141], v[134:137], v[166:169], v[138:141]
	v_mfma_f32_16x16x32_bf16 v[130:133], v[146:149], v[162:165], v[130:133]
	v_mfma_f32_16x16x32_bf16 v[130:133], v[150:153], v[166:169], v[130:133]
	v_mfma_f32_16x16x32_bf16 v[126:129], v[154:157], v[162:165], v[126:129]
	v_mfma_f32_16x16x32_bf16 v[126:129], v[158:161], v[166:169], v[126:129]
	v_mfma_f32_16x16x32_bf16 v[106:109], v[154:157], v[170:173], v[106:109]
	v_mfma_f32_16x16x32_bf16 v[106:109], v[158:161], v[174:177], v[106:109]
	v_mfma_f32_16x16x32_bf16 v[110:113], v[146:149], v[170:173], v[110:113]
	v_mfma_f32_16x16x32_bf16 v[110:113], v[150:153], v[174:177], v[110:113]
	v_mfma_f32_16x16x32_bf16 v[118:121], v[114:117], v[170:173], v[118:121]
	v_mfma_f32_16x16x32_bf16 v[118:121], v[134:137], v[174:177], v[118:121]
	v_mfma_f32_16x16x32_bf16 v[122:125], v[74:77], v[170:173], v[122:125]
	v_mfma_f32_16x16x32_bf16 v[122:125], v[94:97], v[174:177], v[122:125]
	v_mfma_f32_16x16x32_bf16 v[102:105], v[74:77], v[188:191], v[102:105]
	v_mfma_f32_16x16x32_bf16 v[102:105], v[94:97], v[202:205], v[102:105]
	v_mfma_f32_16x16x32_bf16 v[98:101], v[114:117], v[188:191], v[98:101]
	v_mfma_f32_16x16x32_bf16 v[98:101], v[134:137], v[202:205], v[98:101]
	v_mfma_f32_16x16x32_bf16 v[90:93], v[146:149], v[188:191], v[90:93]
	v_mfma_f32_16x16x32_bf16 v[90:93], v[150:153], v[202:205], v[90:93]
	v_mfma_f32_16x16x32_bf16 v[86:89], v[154:157], v[188:191], v[86:89]
	v_mfma_f32_16x16x32_bf16 v[86:89], v[158:161], v[202:205], v[86:89]
	v_mfma_f32_16x16x32_bf16 v[66:69], v[154:157], v[206:209], v[66:69]
	v_mfma_f32_16x16x32_bf16 v[66:69], v[158:161], v[210:213], v[66:69]
	v_mfma_f32_16x16x32_bf16 v[70:73], v[146:149], v[206:209], v[70:73]
	v_mfma_f32_16x16x32_bf16 v[70:73], v[150:153], v[210:213], v[70:73]
	v_mfma_f32_16x16x32_bf16 v[78:81], v[114:117], v[206:209], v[78:81]
	v_mfma_f32_16x16x32_bf16 v[78:81], v[134:137], v[210:213], v[78:81]
	v_mfma_f32_16x16x32_bf16 v[82:85], v[74:77], v[206:209], v[82:85]
	v_mfma_f32_16x16x32_bf16 v[82:85], v[94:97], v[210:213], v[82:85]
	s_setprio 0
	s_barrier
	ds_read_b128 v[162:165], v186 offset:49152
	ds_read_b128 v[166:169], v186 offset:50176
	ds_read_b128 v[170:173], v186 offset:51200
	ds_read_b128 v[174:177], v186 offset:52224
	ds_read_b128 v[188:191], v186 offset:53248
	ds_read_b128 v[202:205], v186 offset:54272
	ds_read_b128 v[206:209], v186 offset:55296
	ds_read_b128 v[210:213], v186 offset:56320
	s_add_u32 s30, s58, 0x80
	s_addc_u32 s31, s59, 0
	s_mov_b32 m0, s94
	s_nop 0
	global_load_lds_dwordx4 v180, s[30:31]
	s_nop 0
	s_mov_b32 m0, s95
	s_nop 0
	global_load_lds_dwordx4 v182, s[30:31]
	s_add_u32 s30, s58, 0x40080
	s_addc_u32 s31, s59, 0
	s_mov_b32 m0, s17
	s_nop 0
	global_load_lds_dwordx4 v180, s[30:31]
	s_nop 0
	s_mov_b32 m0, s53
	s_nop 0
	global_load_lds_dwordx4 v182, s[30:31]
	s_nop 0
	s_mov_b32 m0, s96
	s_nop 0
	global_load_lds_dwordx4 v0, s[56:57]
	s_nop 0
	s_mov_b32 m0, s97
	s_nop 0
	global_load_lds_dwordx4 v181, s[56:57]
	s_waitcnt vmcnt(8)
	s_waitcnt lgkmcnt(0)
	s_barrier
	s_setprio 1
	s_waitcnt lgkmcnt(0)
	v_mfma_f32_16x16x32_bf16 v[62:65], v[74:77], v[162:165], v[62:65]
	v_mfma_f32_16x16x32_bf16 v[62:65], v[94:97], v[166:169], v[62:65]
	v_mfma_f32_16x16x32_bf16 v[58:61], v[114:117], v[162:165], v[58:61]
	v_mfma_f32_16x16x32_bf16 v[58:61], v[134:137], v[166:169], v[58:61]
	v_mfma_f32_16x16x32_bf16 v[54:57], v[146:149], v[162:165], v[54:57]
	v_mfma_f32_16x16x32_bf16 v[54:57], v[150:153], v[166:169], v[54:57]
	v_mfma_f32_16x16x32_bf16 v[50:53], v[154:157], v[162:165], v[50:53]
	v_mfma_f32_16x16x32_bf16 v[50:53], v[158:161], v[166:169], v[50:53]
	v_mfma_f32_16x16x32_bf16 v[34:37], v[154:157], v[170:173], v[34:37]
	v_mfma_f32_16x16x32_bf16 v[34:37], v[158:161], v[174:177], v[34:37]
	v_mfma_f32_16x16x32_bf16 v[38:41], v[146:149], v[170:173], v[38:41]
	v_mfma_f32_16x16x32_bf16 v[38:41], v[150:153], v[174:177], v[38:41]
	v_mfma_f32_16x16x32_bf16 v[42:45], v[114:117], v[170:173], v[42:45]
	v_mfma_f32_16x16x32_bf16 v[42:45], v[134:137], v[174:177], v[42:45]
	v_mfma_f32_16x16x32_bf16 v[46:49], v[74:77], v[170:173], v[46:49]
	v_mfma_f32_16x16x32_bf16 v[46:49], v[94:97], v[174:177], v[46:49]
	v_mfma_f32_16x16x32_bf16 v[30:33], v[74:77], v[188:191], v[30:33]
	v_mfma_f32_16x16x32_bf16 v[30:33], v[94:97], v[202:205], v[30:33]
	v_mfma_f32_16x16x32_bf16 v[26:29], v[114:117], v[188:191], v[26:29]
	v_mfma_f32_16x16x32_bf16 v[26:29], v[134:137], v[202:205], v[26:29]
	v_mfma_f32_16x16x32_bf16 v[22:25], v[146:149], v[188:191], v[22:25]
	v_mfma_f32_16x16x32_bf16 v[22:25], v[150:153], v[202:205], v[22:25]
	v_mfma_f32_16x16x32_bf16 v[18:21], v[154:157], v[188:191], v[18:21]
	v_mfma_f32_16x16x32_bf16 v[18:21], v[158:161], v[202:205], v[18:21]
	v_mfma_f32_16x16x32_bf16 v[2:5], v[154:157], v[206:209], v[2:5]
	v_mfma_f32_16x16x32_bf16 v[2:5], v[158:161], v[210:213], v[2:5]
	v_mfma_f32_16x16x32_bf16 v[6:9], v[146:149], v[206:209], v[6:9]
	v_mfma_f32_16x16x32_bf16 v[6:9], v[150:153], v[210:213], v[6:9]
	v_mfma_f32_16x16x32_bf16 v[10:13], v[114:117], v[206:209], v[10:13]
	v_mfma_f32_16x16x32_bf16 v[10:13], v[134:137], v[210:213], v[10:13]
	v_mfma_f32_16x16x32_bf16 v[14:17], v[74:77], v[206:209], v[14:17]
	v_mfma_f32_16x16x32_bf16 v[14:17], v[94:97], v[210:213], v[14:17]
	s_setprio 0
	s_barrier
	s_add_i32 s50, s50, 2
	s_add_u32 s41, s41, 0x100
	s_addc_u32 s49, s49, 0
	s_add_u32 s92, s92, 0x100
	s_addc_u32 s93, s93, 0
	s_cmp_gt_u32 s50, 13
	s_cbranch_scc0 .LBB0_306
	v_readlane_b32 s4, v254, 46
	v_readlane_b32 s5, v254, 47
	s_and_b64 vcc, exec, s[4:5]
	s_cbranch_vccz .LBB0_309
	s_barrier
; __device__ __forceinline__ unsigned cvt_pk_bf16(float lo, float hi) { unsigned r; asm volatile("v_cvt_pk_bf16_f32 %0, %1, %2" : "=v"(r) : "v"(lo), "v"(hi)); return r; }
; __device__ __forceinline__ float silu_f(float g) { return g * __builtin_amdgcn_rcpf(1.0f + __builtin_amdgcn_exp2f(g * -1.4426950408889634f)); }
;     __device__ __forceinline__ void operator()(const f32x4 (&acc)[2][2][4][2], const Unit& u, int wr, int wc, int fr, int fq) const {
;         const int row0 = u.pm * BM + wr * 64 + fr, col0 = u.pn * HALF + wc * 32 + 8 * fq;
;         float rsv[2][4]; rstd8(ss, row0, rsv);
; #pragma unroll
;         for (int ai = 0; ai < 2; ++ai)
; #pragma unroll
;             for (int m = 0; m < 4; ++m) { const int row = row0 + ai * HALF + m * 16; const float rs = rsv[ai][m];
;                 f32x4 g0 = acc[ai][0][m][0] * rs, g1 = acc[ai][0][m][1] * rs; const f32x4 t0 = acc[ai][1][m][0] * rs, t1 = acc[ai][1][m][1] * rs;
;                 if (silu) {
; #pragma unroll
;                     for (int j = 0; j < 4; ++j) { g0[j] = silu_f(g0[j]); g1[j] = silu_f(g1[j]); } }
;                 g0 = g0 * t0; g1 = g1 * t1;
;                 u32x4 w; w.x = cvt_pk_bf16(g0[0], g0[1]); w.y = cvt_pk_bf16(g0[2], g0[3]); w.z = cvt_pk_bf16(g1[0], g1[1]); w.w = cvt_pk_bf16(g1[2], g1[3]);
;                 *(u32x4*)(O + (size_t)row * ldc + col0 + (size_t)(row >> 12) * adj) = w; }
;     }
.LBB0_309:
	s_branch .Lep_fast
.Lep_join:
	s_cbranch_vccnz .LBB0_302
	v_readlane_b32 s4, v254, 44
	v_readlane_b32 s5, v254, 45
	s_andn2_b64 vcc, exec, s[4:5]
	s_cbranch_vccnz .LBB0_301
	s_barrier
	s_branch .LBB0_301
.Lep_fast:
	s_lshl_b32 s4, s54, 8
	s_add_i32 s4, s4, s89
	v_or_b32_e32 v178, s4, v183
	s_lshl_b32 s5, s0, 1
	v_lshl_or_b32 v179, s48, 7, v184
	s_lshl_b32 s30, s5, 4
	s_mul_i32 s31, s5, 80
	v_mul_lo_u32 v190, v178, s5
	s_lshr_b32 vcc_lo, s4, 12
	s_mul_i32 vcc_lo, vcc_lo, s28
	s_lshl_b32 vcc_lo, vcc_lo, 1
	s_cmp_eq_u32 s54, s98
	v_lshl_add_u32 v190, v179, 1, v190
	v_add_u32_e32 v190, vcc_lo, v190
	s_cbranch_scc1 .Lep_have_rs
	v_lshlrev_b32_e32 v178, 4, v178
	global_load_dwordx4 v[146:149], v178, s[24:25]
	global_load_dwordx4 v[150:153], v178, s[24:25] offset:256
	global_load_dwordx4 v[154:157], v178, s[24:25] offset:512
	global_load_dwordx4 v[158:161], v178, s[24:25] offset:768
	global_load_dwordx4 v[162:165], v178, s[24:25] offset:2048
	global_load_dwordx4 v[166:169], v178, s[24:25] offset:2304
	global_load_dwordx4 v[170:173], v178, s[24:25] offset:2560
	global_load_dwordx4 v[174:177], v178, s[24:25] offset:2816
	s_mov_b32 s98, s54
	s_waitcnt vmcnt(0)
	v_add_f32_e32 v146, v146, v147
	v_add_f32_e32 v148, v148, v149
	v_add_f32_e32 v150, v150, v151
	v_add_f32_e32 v152, v152, v153
	v_add_f32_e32 v154, v154, v155
	v_add_f32_e32 v156, v156, v157
	v_add_f32_e32 v158, v158, v159
	v_add_f32_e32 v160, v160, v161
	v_add_f32_e32 v162, v162, v163
	v_add_f32_e32 v164, v164, v165
	v_add_f32_e32 v166, v166, v167
	v_add_f32_e32 v168, v168, v169
	v_add_f32_e32 v170, v170, v171
	v_add_f32_e32 v172, v172, v173
	v_add_f32_e32 v174, v174, v175
	v_add_f32_e32 v176, v176, v177
	v_add_f32_e32 v146, v146, v148
	v_add_f32_e32 v150, v150, v152
	v_add_f32_e32 v154, v154, v156
	v_add_f32_e32 v158, v158, v160
	v_add_f32_e32 v162, v162, v164
	v_add_f32_e32 v166, v166, v168
	v_add_f32_e32 v170, v170, v172
	v_add_f32_e32 v174, v174, v176
	v_fmamk_f32 v241, v146, 0x3a800000, v224
	v_fmamk_f32 v243, v150, 0x3a800000, v224
	v_fmamk_f32 v245, v154, 0x3a800000, v224
	v_fmamk_f32 v247, v158, 0x3a800000, v224
	v_fmamk_f32 v249, v162, 0x3a800000, v224
	v_fmamk_f32 v251, v166, 0x3a800000, v224
	v_fmamk_f32 v253, v170, 0x3a800000, v224
	v_fmamk_f32 v215, v174, 0x3a800000, v224
	v_rsq_f32_e32 v240, v241
	v_rsq_f32_e32 v242, v243
	v_rsq_f32_e32 v244, v245
	v_rsq_f32_e32 v246, v247
	v_rsq_f32_e32 v248, v249
	v_rsq_f32_e32 v250, v251
	v_rsq_f32_e32 v252, v253
	v_rsq_f32_e32 v214, v215
	s_nop 0
	v_mul_f32_e32 v240, 0xbfb8aa3b, v240
	v_mul_f32_e32 v242, 0xbfb8aa3b, v242
	v_mul_f32_e32 v244, 0xbfb8aa3b, v244
	v_mul_f32_e32 v246, 0xbfb8aa3b, v246
	v_mul_f32_e32 v248, 0xbfb8aa3b, v248
	v_mul_f32_e32 v250, 0xbfb8aa3b, v250
	v_mul_f32_e32 v252, 0xbfb8aa3b, v252
	v_mul_f32_e32 v214, 0xbfb8aa3b, v214
.Lep_have_rs:
	s_and_b64 vcc, exec, s[6:7]
	s_cbranch_vccnz .Lep_nosilu
	v_pk_mul_f32 v[146:147], v[142:143], v[240:241] op_sel_hi:[1,0]
	v_pk_mul_f32 v[148:149], v[144:145], v[240:241] op_sel_hi:[1,0]
	v_pk_mul_f32 v[150:151], v[138:139], v[240:241] op_sel_hi:[1,0]
	v_pk_mul_f32 v[152:153], v[140:141], v[240:241] op_sel_hi:[1,0]
	v_exp_f32_e32 v146, v146
	v_exp_f32_e32 v147, v147
	v_exp_f32_e32 v148, v148
	v_exp_f32_e32 v149, v149
	v_exp_f32_e32 v150, v150
	v_exp_f32_e32 v151, v151
	v_exp_f32_e32 v152, v152
	v_exp_f32_e32 v153, v153
	v_pk_mul_f32 v[142:143], v[142:143], v[130:131]
	v_pk_mul_f32 v[144:145], v[144:145], v[132:133]
	v_pk_mul_f32 v[138:139], v[138:139], v[126:127]
	v_pk_mul_f32 v[140:141], v[140:141], v[128:129]
	v_pk_fma_f32 v[146:147], v[146:147], v[240:241], v[240:241] op_sel:[0,1,1] op_sel_hi:[1,1,1]
	v_pk_fma_f32 v[148:149], v[148:149], v[240:241], v[240:241] op_sel:[0,1,1] op_sel_hi:[1,1,1]
	v_pk_fma_f32 v[150:151], v[150:151], v[240:241], v[240:241] op_sel:[0,1,1] op_sel_hi:[1,1,1]
	v_pk_fma_f32 v[152:153], v[152:153], v[240:241], v[240:241] op_sel:[0,1,1] op_sel_hi:[1,1,1]
	v_rcp_f32_e32 v146, v146
	v_rcp_f32_e32 v147, v147
	v_rcp_f32_e32 v148, v148
	v_rcp_f32_e32 v149, v149
	v_rcp_f32_e32 v150, v150
	v_rcp_f32_e32 v151, v151
	v_rcp_f32_e32 v152, v152
	v_rcp_f32_e32 v153, v153
	v_pk_mul_f32 v[154:155], v[122:123], v[242:243] op_sel_hi:[1,0]
	v_pk_mul_f32 v[156:157], v[124:125], v[242:243] op_sel_hi:[1,0]
	v_pk_mul_f32 v[158:159], v[118:119], v[242:243] op_sel_hi:[1,0]
	v_pk_mul_f32 v[160:161], v[120:121], v[242:243] op_sel_hi:[1,0]
	v_pk_mul_f32 v[142:143], v[142:143], v[146:147]
	v_pk_mul_f32 v[144:145], v[144:145], v[148:149]
	v_pk_mul_f32 v[138:139], v[138:139], v[150:151]
	v_pk_mul_f32 v[140:141], v[140:141], v[152:153]
	v_cvt_pk_bf16_f32 v162, v142, v143
	v_cvt_pk_bf16_f32 v163, v144, v145
	v_cvt_pk_bf16_f32 v164, v138, v139
	v_cvt_pk_bf16_f32 v165, v140, v141
	global_store_dwordx4 v190, v[162:165], s[10:11] sc1
	v_add_u32_e32 v190, s30, v190
	v_exp_f32_e32 v154, v154
	v_exp_f32_e32 v155, v155
	v_exp_f32_e32 v156, v156
	v_exp_f32_e32 v157, v157
	v_exp_f32_e32 v158, v158
	v_exp_f32_e32 v159, v159
	v_exp_f32_e32 v160, v160
	v_exp_f32_e32 v161, v161
	v_pk_mul_f32 v[122:123], v[122:123], v[110:111]
	v_pk_mul_f32 v[124:125], v[124:125], v[112:113]
	v_pk_mul_f32 v[118:119], v[118:119], v[106:107]
	v_pk_mul_f32 v[120:121], v[120:121], v[108:109]
	v_pk_fma_f32 v[154:155], v[154:155], v[242:243], v[242:243] op_sel:[0,1,1] op_sel_hi:[1,1,1]
	v_pk_fma_f32 v[156:157], v[156:157], v[242:243], v[242:243] op_sel:[0,1,1] op_sel_hi:[1,1,1]
	v_pk_fma_f32 v[158:159], v[158:159], v[242:243], v[242:243] op_sel:[0,1,1] op_sel_hi:[1,1,1]
	v_pk_fma_f32 v[160:161], v[160:161], v[242:243], v[242:243] op_sel:[0,1,1] op_sel_hi:[1,1,1]
	v_rcp_f32_e32 v154, v154
	v_rcp_f32_e32 v155, v155
; __device__ __forceinline__ unsigned cvt_pk_bf16(float lo, float hi) { unsigned r; asm volatile("v_cvt_pk_bf16_f32 %0, %1, %2" : "=v"(r) : "v"(lo), "v"(hi)); return r; }
; __device__ __forceinline__ float silu_f(float g) { return g * __builtin_amdgcn_rcpf(1.0f + __builtin_amdgcn_exp2f(g * -1.4426950408889634f)); }
;     __device__ __forceinline__ void operator()(const f32x4 (&acc)[2][2][4][2], const Unit& u, int wr, int wc, int fr, int fq) const {
;     ...
;             for (int m = 0; m < 4; ++m) { const int row = row0 + ai * HALF + m * 16; const float rs = rsv[ai][m];
;                 f32x4 g0 = acc[ai][0][m][0] * rs, g1 = acc[ai][0][m][1] * rs; const f32x4 t0 = acc[ai][1][m][0] * rs, t1 = acc[ai][1][m][1] * rs;
;                 if (silu) {
; #pragma unroll
;                     for (int j = 0; j < 4; ++j) { g0[j] = silu_f(g0[j]); g1[j] = silu_f(g1[j]); } }
;                 g0 = g0 * t0; g1 = g1 * t1;
;                 u32x4 w; w.x = cvt_pk_bf16(g0[0], g0[1]); w.y = cvt_pk_bf16(g0[2], g0[3]); w.z = cvt_pk_bf16(g1[0], g1[1]); w.w = cvt_pk_bf16(g1[2], g1[3]);
;                 *(u32x4*)(O + (size_t)row * ldc + col0 + (size_t)(row >> 12) * adj) = w; }
	v_rcp_f32_e32 v156, v156
	v_rcp_f32_e32 v157, v157
	v_rcp_f32_e32 v158, v158
	v_rcp_f32_e32 v159, v159
	v_rcp_f32_e32 v160, v160
	v_rcp_f32_e32 v161, v161
	v_pk_mul_f32 v[146:147], v[102:103], v[244:245] op_sel_hi:[1,0]
	v_pk_mul_f32 v[148:149], v[104:105], v[244:245] op_sel_hi:[1,0]
	v_pk_mul_f32 v[150:151], v[98:99], v[244:245] op_sel_hi:[1,0]
	v_pk_mul_f32 v[152:153], v[100:101], v[244:245] op_sel_hi:[1,0]
	v_pk_mul_f32 v[122:123], v[122:123], v[154:155]
	v_pk_mul_f32 v[124:125], v[124:125], v[156:157]
	v_pk_mul_f32 v[118:119], v[118:119], v[158:159]
	v_pk_mul_f32 v[120:121], v[120:121], v[160:161]
	v_cvt_pk_bf16_f32 v166, v122, v123
	v_cvt_pk_bf16_f32 v167, v124, v125
	v_cvt_pk_bf16_f32 v168, v118, v119
	v_cvt_pk_bf16_f32 v169, v120, v121
	global_store_dwordx4 v190, v[166:169], s[10:11] sc1
	v_add_u32_e32 v190, s30, v190
	v_exp_f32_e32 v146, v146
	v_exp_f32_e32 v147, v147
	v_exp_f32_e32 v148, v148
	v_exp_f32_e32 v149, v149
	v_exp_f32_e32 v150, v150
	v_exp_f32_e32 v151, v151
	v_exp_f32_e32 v152, v152
	v_exp_f32_e32 v153, v153
	v_pk_mul_f32 v[102:103], v[102:103], v[90:91]
	v_pk_mul_f32 v[104:105], v[104:105], v[92:93]
	v_pk_mul_f32 v[98:99], v[98:99], v[86:87]
	v_pk_mul_f32 v[100:101], v[100:101], v[88:89]
	v_pk_fma_f32 v[146:147], v[146:147], v[244:245], v[244:245] op_sel:[0,1,1] op_sel_hi:[1,1,1]
	v_pk_fma_f32 v[148:149], v[148:149], v[244:245], v[244:245] op_sel:[0,1,1] op_sel_hi:[1,1,1]
	v_pk_fma_f32 v[150:151], v[150:151], v[244:245], v[244:245] op_sel:[0,1,1] op_sel_hi:[1,1,1]
	v_pk_fma_f32 v[152:153], v[152:153], v[244:245], v[244:245] op_sel:[0,1,1] op_sel_hi:[1,1,1]
	v_rcp_f32_e32 v146, v146
	v_rcp_f32_e32 v147, v147
	v_rcp_f32_e32 v148, v148
	v_rcp_f32_e32 v149, v149
	v_rcp_f32_e32 v150, v150
	v_rcp_f32_e32 v151, v151
	v_rcp_f32_e32 v152, v152
	v_rcp_f32_e32 v153, v153
	v_pk_mul_f32 v[154:155], v[82:83], v[246:247] op_sel_hi:[1,0]
	v_pk_mul_f32 v[156:157], v[84:85], v[246:247] op_sel_hi:[1,0]
	v_pk_mul_f32 v[158:159], v[78:79], v[246:247] op_sel_hi:[1,0]
	v_pk_mul_f32 v[160:161], v[80:81], v[246:247] op_sel_hi:[1,0]
	v_pk_mul_f32 v[102:103], v[102:103], v[146:147]
	v_pk_mul_f32 v[104:105], v[104:105], v[148:149]
	v_pk_mul_f32 v[98:99], v[98:99], v[150:151]
	v_pk_mul_f32 v[100:101], v[100:101], v[152:153]
	v_cvt_pk_bf16_f32 v162, v102, v103
	v_cvt_pk_bf16_f32 v163, v104, v105
	v_cvt_pk_bf16_f32 v164, v98, v99
	v_cvt_pk_bf16_f32 v165, v100, v101
	global_store_dwordx4 v190, v[162:165], s[10:11] sc1
	v_add_u32_e32 v190, s30, v190
	v_exp_f32_e32 v154, v154
	v_exp_f32_e32 v155, v155
	v_exp_f32_e32 v156, v156
	v_exp_f32_e32 v157, v157
	v_exp_f32_e32 v158, v158
	v_exp_f32_e32 v159, v159
	v_exp_f32_e32 v160, v160
	v_exp_f32_e32 v161, v161
	v_pk_mul_f32 v[82:83], v[82:83], v[70:71]
	v_pk_mul_f32 v[84:85], v[84:85], v[72:73]
	v_pk_mul_f32 v[78:79], v[78:79], v[66:67]
	v_pk_mul_f32 v[80:81], v[80:81], v[68:69]
	v_pk_fma_f32 v[154:155], v[154:155], v[246:247], v[246:247] op_sel:[0,1,1] op_sel_hi:[1,1,1]
	v_pk_fma_f32 v[156:157], v[156:157], v[246:247], v[246:247] op_sel:[0,1,1] op_sel_hi:[1,1,1]
	v_pk_fma_f32 v[158:159], v[158:159], v[246:247], v[246:247] op_sel:[0,1,1] op_sel_hi:[1,1,1]
	v_pk_fma_f32 v[160:161], v[160:161], v[246:247], v[246:247] op_sel:[0,1,1] op_sel_hi:[1,1,1]
	v_rcp_f32_e32 v154, v154
	v_rcp_f32_e32 v155, v155
	v_rcp_f32_e32 v156, v156
	v_rcp_f32_e32 v157, v157
	v_rcp_f32_e32 v158, v158
	v_rcp_f32_e32 v159, v159
	v_rcp_f32_e32 v160, v160
	v_rcp_f32_e32 v161, v161
	v_pk_mul_f32 v[146:147], v[62:63], v[248:249] op_sel_hi:[1,0]
	v_pk_mul_f32 v[148:149], v[64:65], v[248:249] op_sel_hi:[1,0]
	v_pk_mul_f32 v[150:151], v[58:59], v[248:249] op_sel_hi:[1,0]
	v_pk_mul_f32 v[152:153], v[60:61], v[248:249] op_sel_hi:[1,0]
	v_pk_mul_f32 v[82:83], v[82:83], v[154:155]
	v_pk_mul_f32 v[84:85], v[84:85], v[156:157]
	v_pk_mul_f32 v[78:79], v[78:79], v[158:159]
	v_pk_mul_f32 v[80:81], v[80:81], v[160:161]
	v_cvt_pk_bf16_f32 v166, v82, v83
	v_cvt_pk_bf16_f32 v167, v84, v85
	v_cvt_pk_bf16_f32 v168, v78, v79
	v_cvt_pk_bf16_f32 v169, v80, v81
	global_store_dwordx4 v190, v[166:169], s[10:11] sc1
	v_add_u32_e32 v190, s31, v190
	v_exp_f32_e32 v146, v146
	v_exp_f32_e32 v147, v147
	v_exp_f32_e32 v148, v148
	v_exp_f32_e32 v149, v149
	v_exp_f32_e32 v150, v150
	v_exp_f32_e32 v151, v151
	v_exp_f32_e32 v152, v152
	v_exp_f32_e32 v153, v153
	v_pk_mul_f32 v[62:63], v[62:63], v[54:55]
	v_pk_mul_f32 v[64:65], v[64:65], v[56:57]
	v_pk_mul_f32 v[58:59], v[58:59], v[50:51]
	v_pk_mul_f32 v[60:61], v[60:61], v[52:53]
	v_pk_fma_f32 v[146:147], v[146:147], v[248:249], v[248:249] op_sel:[0,1,1] op_sel_hi:[1,1,1]
	v_pk_fma_f32 v[148:149], v[148:149], v[248:249], v[248:249] op_sel:[0,1,1] op_sel_hi:[1,1,1]
	v_pk_fma_f32 v[150:151], v[150:151], v[248:249], v[248:249] op_sel:[0,1,1] op_sel_hi:[1,1,1]
	v_pk_fma_f32 v[152:153], v[152:153], v[248:249], v[248:249] op_sel:[0,1,1] op_sel_hi:[1,1,1]
	v_rcp_f32_e32 v146, v146
	v_rcp_f32_e32 v147, v147
	v_rcp_f32_e32 v148, v148
	v_rcp_f32_e32 v149, v149
	v_rcp_f32_e32 v150, v150
	v_rcp_f32_e32 v151, v151
	v_rcp_f32_e32 v152, v152
	v_rcp_f32_e32 v153, v153
	v_pk_mul_f32 v[154:155], v[46:47], v[250:251] op_sel_hi:[1,0]
	v_pk_mul_f32 v[156:157], v[48:49], v[250:251] op_sel_hi:[1,0]
	v_pk_mul_f32 v[158:159], v[42:43], v[250:251] op_sel_hi:[1,0]
	v_pk_mul_f32 v[160:161], v[44:45], v[250:251] op_sel_hi:[1,0]
	v_pk_mul_f32 v[62:63], v[62:63], v[146:147]
	v_pk_mul_f32 v[64:65], v[64:65], v[148:149]
	v_pk_mul_f32 v[58:59], v[58:59], v[150:151]
	v_pk_mul_f32 v[60:61], v[60:61], v[152:153]
	v_cvt_pk_bf16_f32 v162, v62, v63
	v_cvt_pk_bf16_f32 v163, v64, v65
	v_cvt_pk_bf16_f32 v164, v58, v59
	v_cvt_pk_bf16_f32 v165, v60, v61
; __device__ __forceinline__ unsigned cvt_pk_bf16(float lo, float hi) { unsigned r; asm volatile("v_cvt_pk_bf16_f32 %0, %1, %2" : "=v"(r) : "v"(lo), "v"(hi)); return r; }
; __device__ __forceinline__ float silu_f(float g) { return g * __builtin_amdgcn_rcpf(1.0f + __builtin_amdgcn_exp2f(g * -1.4426950408889634f)); }
;     __device__ __forceinline__ void operator()(const f32x4 (&acc)[2][2][4][2], const Unit& u, int wr, int wc, int fr, int fq) const {
;     ...
;             for (int m = 0; m < 4; ++m) { const int row = row0 + ai * HALF + m * 16; const float rs = rsv[ai][m];
;                 f32x4 g0 = acc[ai][0][m][0] * rs, g1 = acc[ai][0][m][1] * rs; const f32x4 t0 = acc[ai][1][m][0] * rs, t1 = acc[ai][1][m][1] * rs;
;                 if (silu) {
; #pragma unroll
;                     for (int j = 0; j < 4; ++j) { g0[j] = silu_f(g0[j]); g1[j] = silu_f(g1[j]); } }
;                 g0 = g0 * t0; g1 = g1 * t1;
;                 u32x4 w; w.x = cvt_pk_bf16(g0[0], g0[1]); w.y = cvt_pk_bf16(g0[2], g0[3]); w.z = cvt_pk_bf16(g1[0], g1[1]); w.w = cvt_pk_bf16(g1[2], g1[3]);
;                 *(u32x4*)(O + (size_t)row * ldc + col0 + (size_t)(row >> 12) * adj) = w; }
;     }
; template <class Epi, bool ALIGN_EPI>
; __device__ __forceinline__ void gemm_phase(LAS unsigned char* lds, const Gemm g, const StaticOrder& S, const Epi& E) {
;     ...
;         E(acc, cur, wr, wc, fr, fq);
;         if (!has_next) break;
	global_store_dwordx4 v190, v[162:165], s[10:11] sc1
	v_add_u32_e32 v190, s30, v190
	v_exp_f32_e32 v154, v154
	v_exp_f32_e32 v155, v155
	v_exp_f32_e32 v156, v156
	v_exp_f32_e32 v157, v157
	v_exp_f32_e32 v158, v158
	v_exp_f32_e32 v159, v159
	v_exp_f32_e32 v160, v160
	v_exp_f32_e32 v161, v161
	v_pk_mul_f32 v[46:47], v[46:47], v[38:39]
	v_pk_mul_f32 v[48:49], v[48:49], v[40:41]
	v_pk_mul_f32 v[42:43], v[42:43], v[34:35]
	v_pk_mul_f32 v[44:45], v[44:45], v[36:37]
	v_pk_fma_f32 v[154:155], v[154:155], v[250:251], v[250:251] op_sel:[0,1,1] op_sel_hi:[1,1,1]
	v_pk_fma_f32 v[156:157], v[156:157], v[250:251], v[250:251] op_sel:[0,1,1] op_sel_hi:[1,1,1]
	v_pk_fma_f32 v[158:159], v[158:159], v[250:251], v[250:251] op_sel:[0,1,1] op_sel_hi:[1,1,1]
	v_pk_fma_f32 v[160:161], v[160:161], v[250:251], v[250:251] op_sel:[0,1,1] op_sel_hi:[1,1,1]
	v_rcp_f32_e32 v154, v154
	v_rcp_f32_e32 v155, v155
	v_rcp_f32_e32 v156, v156
	v_rcp_f32_e32 v157, v157
	v_rcp_f32_e32 v158, v158
	v_rcp_f32_e32 v159, v159
	v_rcp_f32_e32 v160, v160
	v_rcp_f32_e32 v161, v161
	v_pk_mul_f32 v[146:147], v[30:31], v[252:253] op_sel_hi:[1,0]
	v_pk_mul_f32 v[148:149], v[32:33], v[252:253] op_sel_hi:[1,0]
	v_pk_mul_f32 v[150:151], v[26:27], v[252:253] op_sel_hi:[1,0]
	v_pk_mul_f32 v[152:153], v[28:29], v[252:253] op_sel_hi:[1,0]
	v_pk_mul_f32 v[46:47], v[46:47], v[154:155]
	v_pk_mul_f32 v[48:49], v[48:49], v[156:157]
	v_pk_mul_f32 v[42:43], v[42:43], v[158:159]
	v_pk_mul_f32 v[44:45], v[44:45], v[160:161]
	v_cvt_pk_bf16_f32 v166, v46, v47
	v_cvt_pk_bf16_f32 v167, v48, v49
	v_cvt_pk_bf16_f32 v168, v42, v43
	v_cvt_pk_bf16_f32 v169, v44, v45
	global_store_dwordx4 v190, v[166:169], s[10:11] sc1
	v_add_u32_e32 v190, s30, v190
	v_exp_f32_e32 v146, v146
	v_exp_f32_e32 v147, v147
	v_exp_f32_e32 v148, v148
	v_exp_f32_e32 v149, v149
	v_exp_f32_e32 v150, v150
	v_exp_f32_e32 v151, v151
	v_exp_f32_e32 v152, v152
	v_exp_f32_e32 v153, v153
	v_pk_mul_f32 v[30:31], v[30:31], v[22:23]
	v_pk_mul_f32 v[32:33], v[32:33], v[24:25]
	v_pk_mul_f32 v[26:27], v[26:27], v[18:19]
	v_pk_mul_f32 v[28:29], v[28:29], v[20:21]
	v_pk_fma_f32 v[146:147], v[146:147], v[252:253], v[252:253] op_sel:[0,1,1] op_sel_hi:[1,1,1]
	v_pk_fma_f32 v[148:149], v[148:149], v[252:253], v[252:253] op_sel:[0,1,1] op_sel_hi:[1,1,1]
	v_pk_fma_f32 v[150:151], v[150:151], v[252:253], v[252:253] op_sel:[0,1,1] op_sel_hi:[1,1,1]
	v_pk_fma_f32 v[152:153], v[152:153], v[252:253], v[252:253] op_sel:[0,1,1] op_sel_hi:[1,1,1]
	v_rcp_f32_e32 v146, v146
	v_rcp_f32_e32 v147, v147
	v_rcp_f32_e32 v148, v148
	v_rcp_f32_e32 v149, v149
	v_rcp_f32_e32 v150, v150
	v_rcp_f32_e32 v151, v151
	v_rcp_f32_e32 v152, v152
	v_rcp_f32_e32 v153, v153
	v_pk_mul_f32 v[154:155], v[14:15], v[214:215] op_sel_hi:[1,0]
	v_pk_mul_f32 v[156:157], v[16:17], v[214:215] op_sel_hi:[1,0]
	v_pk_mul_f32 v[158:159], v[10:11], v[214:215] op_sel_hi:[1,0]
	v_pk_mul_f32 v[160:161], v[12:13], v[214:215] op_sel_hi:[1,0]
	v_pk_mul_f32 v[30:31], v[30:31], v[146:147]
	v_pk_mul_f32 v[32:33], v[32:33], v[148:149]
	v_pk_mul_f32 v[26:27], v[26:27], v[150:151]
	v_pk_mul_f32 v[28:29], v[28:29], v[152:153]
	v_cvt_pk_bf16_f32 v162, v30, v31
	v_cvt_pk_bf16_f32 v163, v32, v33
	v_cvt_pk_bf16_f32 v164, v26, v27
	v_cvt_pk_bf16_f32 v165, v28, v29
	global_store_dwordx4 v190, v[162:165], s[10:11] sc1
	v_add_u32_e32 v190, s30, v190
	v_exp_f32_e32 v154, v154
	v_exp_f32_e32 v155, v155
	v_exp_f32_e32 v156, v156
	v_exp_f32_e32 v157, v157
	v_exp_f32_e32 v158, v158
	v_exp_f32_e32 v159, v159
	v_exp_f32_e32 v160, v160
	v_exp_f32_e32 v161, v161
	v_pk_mul_f32 v[14:15], v[14:15], v[6:7]
	v_pk_mul_f32 v[16:17], v[16:17], v[8:9]
	v_pk_mul_f32 v[10:11], v[10:11], v[2:3]
	v_pk_mul_f32 v[12:13], v[12:13], v[4:5]
	v_pk_fma_f32 v[154:155], v[154:155], v[214:215], v[214:215] op_sel:[0,1,1] op_sel_hi:[1,1,1]
	v_pk_fma_f32 v[156:157], v[156:157], v[214:215], v[214:215] op_sel:[0,1,1] op_sel_hi:[1,1,1]
	v_pk_fma_f32 v[158:159], v[158:159], v[214:215], v[214:215] op_sel:[0,1,1] op_sel_hi:[1,1,1]
	v_pk_fma_f32 v[160:161], v[160:161], v[214:215], v[214:215] op_sel:[0,1,1] op_sel_hi:[1,1,1]
	v_rcp_f32_e32 v154, v154
	v_rcp_f32_e32 v155, v155
	v_rcp_f32_e32 v156, v156
	v_rcp_f32_e32 v157, v157
	v_rcp_f32_e32 v158, v158
	v_rcp_f32_e32 v159, v159
	v_rcp_f32_e32 v160, v160
	v_rcp_f32_e32 v161, v161
	v_pk_mul_f32 v[14:15], v[14:15], v[154:155]
	v_pk_mul_f32 v[16:17], v[16:17], v[156:157]
	v_pk_mul_f32 v[10:11], v[10:11], v[158:159]
	v_pk_mul_f32 v[12:13], v[12:13], v[160:161]
	v_cvt_pk_bf16_f32 v166, v14, v15
	v_cvt_pk_bf16_f32 v167, v16, v17
	v_cvt_pk_bf16_f32 v168, v10, v11
	v_cvt_pk_bf16_f32 v169, v12, v13
	global_store_dwordx4 v190, v[166:169], s[10:11] sc1
	s_andn2_b64 vcc, exec, s[8:9]
	s_mov_b64 s[4:5], -1
	s_branch .Lep_join
; __device__ __forceinline__ unsigned cvt_pk_bf16(float lo, float hi) { unsigned r; asm volatile("v_cvt_pk_bf16_f32 %0, %1, %2" : "=v"(r) : "v"(lo), "v"(hi)); return r; }
; __device__ __forceinline__ float silu_f(float g) { return g * __builtin_amdgcn_rcpf(1.0f + __builtin_amdgcn_exp2f(g * -1.4426950408889634f)); }
;     __device__ __forceinline__ void operator()(const f32x4 (&acc)[2][2][4][2], const Unit& u, int wr, int wc, int fr, int fq) const {
;     ...
;             for (int m = 0; m < 4; ++m) { const int row = row0 + ai * HALF + m * 16; const float rs = rsv[ai][m];
;                 f32x4 g0 = acc[ai][0][m][0] * rs, g1 = acc[ai][0][m][1] * rs; const f32x4 t0 = acc[ai][1][m][0] * rs, t1 = acc[ai][1][m][1] * rs;
;                 if (silu) {
; #pragma unroll
;                     for (int j = 0; j < 4; ++j) { g0[j] = silu_f(g0[j]); g1[j] = silu_f(g1[j]); } }
;                 g0 = g0 * t0; g1 = g1 * t1;
;                 u32x4 w; w.x = cvt_pk_bf16(g0[0], g0[1]); w.y = cvt_pk_bf16(g0[2], g0[3]); w.z = cvt_pk_bf16(g1[0], g1[1]); w.w = cvt_pk_bf16(g1[2], g1[3]);
;                 *(u32x4*)(O + (size_t)row * ldc + col0 + (size_t)(row >> 12) * adj) = w; }
.Lep_nosilu:
	v_mul_f32_e32 v170, v240, v240
	v_pk_mul_f32 v[142:143], v[142:143], v[130:131]
	v_pk_mul_f32 v[144:145], v[144:145], v[132:133]
	v_pk_mul_f32 v[138:139], v[138:139], v[126:127]
	v_pk_mul_f32 v[140:141], v[140:141], v[128:129]
	v_mul_f32_e32 v170, 0x3ef5fdf0, v170
	v_pk_mul_f32 v[142:143], v[142:143], v[170:171] op_sel_hi:[1,0]
	v_pk_mul_f32 v[144:145], v[144:145], v[170:171] op_sel_hi:[1,0]
	v_pk_mul_f32 v[138:139], v[138:139], v[170:171] op_sel_hi:[1,0]
	v_pk_mul_f32 v[140:141], v[140:141], v[170:171] op_sel_hi:[1,0]
	v_cvt_pk_bf16_f32 v162, v142, v143
	v_cvt_pk_bf16_f32 v163, v144, v145
	v_cvt_pk_bf16_f32 v164, v138, v139
	v_cvt_pk_bf16_f32 v165, v140, v141
	global_store_dwordx4 v190, v[162:165], s[10:11]
	v_add_u32_e32 v190, s30, v190
	v_mul_f32_e32 v170, v242, v242
	v_pk_mul_f32 v[122:123], v[122:123], v[110:111]
	v_pk_mul_f32 v[124:125], v[124:125], v[112:113]
	v_pk_mul_f32 v[118:119], v[118:119], v[106:107]
	v_pk_mul_f32 v[120:121], v[120:121], v[108:109]
	v_mul_f32_e32 v170, 0x3ef5fdf0, v170
	v_pk_mul_f32 v[122:123], v[122:123], v[170:171] op_sel_hi:[1,0]
	v_pk_mul_f32 v[124:125], v[124:125], v[170:171] op_sel_hi:[1,0]
	v_pk_mul_f32 v[118:119], v[118:119], v[170:171] op_sel_hi:[1,0]
	v_pk_mul_f32 v[120:121], v[120:121], v[170:171] op_sel_hi:[1,0]
	v_cvt_pk_bf16_f32 v166, v122, v123
	v_cvt_pk_bf16_f32 v167, v124, v125
	v_cvt_pk_bf16_f32 v168, v118, v119
	v_cvt_pk_bf16_f32 v169, v120, v121
	global_store_dwordx4 v190, v[166:169], s[10:11]
	v_add_u32_e32 v190, s30, v190
	v_mul_f32_e32 v170, v244, v244
	v_pk_mul_f32 v[102:103], v[102:103], v[90:91]
	v_pk_mul_f32 v[104:105], v[104:105], v[92:93]
	v_pk_mul_f32 v[98:99], v[98:99], v[86:87]
	v_pk_mul_f32 v[100:101], v[100:101], v[88:89]
	v_mul_f32_e32 v170, 0x3ef5fdf0, v170
	v_pk_mul_f32 v[102:103], v[102:103], v[170:171] op_sel_hi:[1,0]
	v_pk_mul_f32 v[104:105], v[104:105], v[170:171] op_sel_hi:[1,0]
	v_pk_mul_f32 v[98:99], v[98:99], v[170:171] op_sel_hi:[1,0]
	v_pk_mul_f32 v[100:101], v[100:101], v[170:171] op_sel_hi:[1,0]
	v_cvt_pk_bf16_f32 v162, v102, v103
	v_cvt_pk_bf16_f32 v163, v104, v105
	v_cvt_pk_bf16_f32 v164, v98, v99
	v_cvt_pk_bf16_f32 v165, v100, v101
	global_store_dwordx4 v190, v[162:165], s[10:11]
	v_add_u32_e32 v190, s30, v190
	v_mul_f32_e32 v170, v246, v246
	v_pk_mul_f32 v[82:83], v[82:83], v[70:71]
	v_pk_mul_f32 v[84:85], v[84:85], v[72:73]
	v_pk_mul_f32 v[78:79], v[78:79], v[66:67]
	v_pk_mul_f32 v[80:81], v[80:81], v[68:69]
	v_mul_f32_e32 v170, 0x3ef5fdf0, v170
	v_pk_mul_f32 v[82:83], v[82:83], v[170:171] op_sel_hi:[1,0]
	v_pk_mul_f32 v[84:85], v[84:85], v[170:171] op_sel_hi:[1,0]
	v_pk_mul_f32 v[78:79], v[78:79], v[170:171] op_sel_hi:[1,0]
	v_pk_mul_f32 v[80:81], v[80:81], v[170:171] op_sel_hi:[1,0]
	v_cvt_pk_bf16_f32 v166, v82, v83
	v_cvt_pk_bf16_f32 v167, v84, v85
	v_cvt_pk_bf16_f32 v168, v78, v79
	v_cvt_pk_bf16_f32 v169, v80, v81
	global_store_dwordx4 v190, v[166:169], s[10:11]
	v_add_u32_e32 v190, s31, v190
	v_mul_f32_e32 v170, v248, v248
	v_pk_mul_f32 v[62:63], v[62:63], v[54:55]
	v_pk_mul_f32 v[64:65], v[64:65], v[56:57]
	v_pk_mul_f32 v[58:59], v[58:59], v[50:51]
	v_pk_mul_f32 v[60:61], v[60:61], v[52:53]
	v_mul_f32_e32 v170, 0x3ef5fdf0, v170
	v_pk_mul_f32 v[62:63], v[62:63], v[170:171] op_sel_hi:[1,0]
	v_pk_mul_f32 v[64:65], v[64:65], v[170:171] op_sel_hi:[1,0]
	v_pk_mul_f32 v[58:59], v[58:59], v[170:171] op_sel_hi:[1,0]
	v_pk_mul_f32 v[60:61], v[60:61], v[170:171] op_sel_hi:[1,0]
	v_cvt_pk_bf16_f32 v162, v62, v63
	v_cvt_pk_bf16_f32 v163, v64, v65
	v_cvt_pk_bf16_f32 v164, v58, v59
	v_cvt_pk_bf16_f32 v165, v60, v61
	global_store_dwordx4 v190, v[162:165], s[10:11]
	v_add_u32_e32 v190, s30, v190
	v_mul_f32_e32 v170, v250, v250
	v_pk_mul_f32 v[46:47], v[46:47], v[38:39]
	v_pk_mul_f32 v[48:49], v[48:49], v[40:41]
	v_pk_mul_f32 v[42:43], v[42:43], v[34:35]
	v_pk_mul_f32 v[44:45], v[44:45], v[36:37]
	v_mul_f32_e32 v170, 0x3ef5fdf0, v170
	v_pk_mul_f32 v[46:47], v[46:47], v[170:171] op_sel_hi:[1,0]
	v_pk_mul_f32 v[48:49], v[48:49], v[170:171] op_sel_hi:[1,0]
	v_pk_mul_f32 v[42:43], v[42:43], v[170:171] op_sel_hi:[1,0]
	v_pk_mul_f32 v[44:45], v[44:45], v[170:171] op_sel_hi:[1,0]
	v_cvt_pk_bf16_f32 v166, v46, v47
	v_cvt_pk_bf16_f32 v167, v48, v49
	v_cvt_pk_bf16_f32 v168, v42, v43
	v_cvt_pk_bf16_f32 v169, v44, v45
	global_store_dwordx4 v190, v[166:169], s[10:11]
	v_add_u32_e32 v190, s30, v190
	v_mul_f32_e32 v170, v252, v252
	v_pk_mul_f32 v[30:31], v[30:31], v[22:23]
	v_pk_mul_f32 v[32:33], v[32:33], v[24:25]
	v_pk_mul_f32 v[26:27], v[26:27], v[18:19]
	v_pk_mul_f32 v[28:29], v[28:29], v[20:21]
	v_mul_f32_e32 v170, 0x3ef5fdf0, v170
	v_pk_mul_f32 v[30:31], v[30:31], v[170:171] op_sel_hi:[1,0]
	v_pk_mul_f32 v[32:33], v[32:33], v[170:171] op_sel_hi:[1,0]
	v_pk_mul_f32 v[26:27], v[26:27], v[170:171] op_sel_hi:[1,0]
	v_pk_mul_f32 v[28:29], v[28:29], v[170:171] op_sel_hi:[1,0]
	v_cvt_pk_bf16_f32 v162, v30, v31
	v_cvt_pk_bf16_f32 v163, v32, v33
	v_cvt_pk_bf16_f32 v164, v26, v27
	v_cvt_pk_bf16_f32 v165, v28, v29
	global_store_dwordx4 v190, v[162:165], s[10:11]
	v_add_u32_e32 v190, s30, v190
	v_mul_f32_e32 v170, v214, v214
	v_pk_mul_f32 v[14:15], v[14:15], v[6:7]
	v_pk_mul_f32 v[16:17], v[16:17], v[8:9]
	v_pk_mul_f32 v[10:11], v[10:11], v[2:3]
	v_pk_mul_f32 v[12:13], v[12:13], v[4:5]
	v_mul_f32_e32 v170, 0x3ef5fdf0, v170
	v_pk_mul_f32 v[14:15], v[14:15], v[170:171] op_sel_hi:[1,0]
	v_pk_mul_f32 v[16:17], v[16:17], v[170:171] op_sel_hi:[1,0]
	v_pk_mul_f32 v[10:11], v[10:11], v[170:171] op_sel_hi:[1,0]
	v_pk_mul_f32 v[12:13], v[12:13], v[170:171] op_sel_hi:[1,0]
	v_cvt_pk_bf16_f32 v166, v14, v15
	v_cvt_pk_bf16_f32 v167, v16, v17
	v_cvt_pk_bf16_f32 v168, v10, v11
	v_cvt_pk_bf16_f32 v169, v12, v13
	global_store_dwordx4 v190, v[166:169], s[10:11]
	s_andn2_b64 vcc, exec, s[8:9]
	s_mov_b64 s[4:5], -1
	s_branch .Lep_join
